# one static s_setprio 1 for waves 0-3 at kernel entry (older half), no other setprio
# speedup vs baseline: 1.0051x; 1.0026x over previous
_Z9trunk_fwd4Args:
	v_readfirstlane_b32 s100, v0
	s_nop 3
	s_and_b32 s100, s100, 0x3ff
	s_lshr_b32 s100, s100, 6
	s_cmp_lt_u32 s100, 4
	s_cbranch_scc0 .Lprio_done
	s_setprio 1
